# hand-written fast path for the in-stream top-k prune: linear bins over the key range, one LDS histogram pass without the bin-0 atomics, compiled exact prune kept as fallback; batch mark 576
# speedup vs baseline: 1.0687x; 1.0389x over previous
.Lrd_app7:
.LBB0_138:
	s_or_b64 exec, exec, s[2:3]
	s_waitcnt lgkmcnt(0)
	s_barrier
	s_mov_b64 s[2:3], 0
	s_and_saveexec_b64 s[6:7], s[4:5]
	s_cbranch_execz .LBB0_140
	ds_read_b32 v40, v157
	s_movk_i32 s2, 0x280
	s_waitcnt lgkmcnt(0)
	v_cmp_lt_i32_e32 vcc, s2, v40
	s_and_b64 s[2:3], vcc, exec
	s_cmp_eq_u64 s[2:3], 0
	s_cbranch_scc1 .LBB0_140
	s_movk_i32 s2, 576
	v_cmp_lt_i32_e32 vcc, s2, v40
	s_and_b64 s[2:3], vcc, exec

.LBB0_144:
	s_and_b32 s2, s7, 3
	v_cmp_eq_u32_e32 vcc, s2, v43
	s_and_saveexec_b64 s[2:3], vcc
	s_cbranch_execz .LBB0_143
	s_ff1_i32_b32 s8, s6
	s_mul_i32 s9, s8, 0xc00
	s_mul_i32 s10, s8, 0x600
	s_add_i32 s10, s10, 0x18000
	s_lshl_b32 s11, s8, 2
	s_add_i32 s11, s11, 0x24000
	v_mov_b32_e32 v40, s11
	ds_read_b32 v92, v40
	s_waitcnt lgkmcnt(0)
	v_readfirstlane_b32 s12, v92
	s_add_i32 s13, s12, -1
	v_min_u32_e32 v93, s13, v190
	v_lshl_add_u32 v94, v93, 2, s9
	v_lshl_add_u32 v93, v93, 1, s10
	ds_read_b32 v161, v94
	ds_read_u16 v142, v93
	v_min_u32_e32 v95, s13, v185
	v_lshl_add_u32 v120, v95, 2, s9
	v_lshl_add_u32 v95, v95, 1, s10
	ds_read_b32 v162, v120
	ds_read_u16 v143, v95
	v_min_u32_e32 v93, s13, v192
	v_lshl_add_u32 v94, v93, 2, s9
	v_lshl_add_u32 v93, v93, 1, s10
	ds_read_b32 v163, v94
	ds_read_u16 v144, v93
	v_min_u32_e32 v95, s13, v191
	v_lshl_add_u32 v120, v95, 2, s9
	v_lshl_add_u32 v95, v95, 1, s10
	ds_read_b32 v164, v120
	ds_read_u16 v145, v95
	v_min_u32_e32 v93, s13, v0
	v_lshl_add_u32 v94, v93, 2, s9
	v_lshl_add_u32 v93, v93, 1, s10
	ds_read_b32 v165, v94
	ds_read_u16 v146, v93
	v_min_u32_e32 v95, s13, v1
	v_lshl_add_u32 v120, v95, 2, s9
	v_lshl_add_u32 v95, v95, 1, s10
	ds_read_b32 v166, v120
	ds_read_u16 v148, v95
	v_min_u32_e32 v93, s13, v2
	v_lshl_add_u32 v94, v93, 2, s9
	v_lshl_add_u32 v93, v93, 1, s10
	ds_read_b32 v167, v94
	ds_read_u16 v149, v93
	v_min_u32_e32 v95, s13, v3
	v_lshl_add_u32 v120, v95, 2, s9
	v_lshl_add_u32 v95, v95, 1, s10
	ds_read_b32 v168, v120
	ds_read_u16 v150, v95
	v_min_u32_e32 v93, s13, v6
	v_lshl_add_u32 v94, v93, 2, s9
	v_lshl_add_u32 v93, v93, 1, s10
	ds_read_b32 v169, v94
	ds_read_u16 v152, v93
	v_min_u32_e32 v95, s13, v7
	v_lshl_add_u32 v120, v95, 2, s9
	v_lshl_add_u32 v95, v95, 1, s10
	ds_read_b32 v170, v120
	ds_read_u16 v153, v95
	v_min_u32_e32 v93, s13, v4
	v_lshl_add_u32 v94, v93, 2, s9
	v_lshl_add_u32 v93, v93, 1, s10
	ds_read_b32 v171, v94
	ds_read_u16 v159, v93
	v_min_u32_e32 v95, s13, v5
	v_lshl_add_u32 v120, v95, 2, s9
	v_lshl_add_u32 v95, v95, 1, s10
	ds_read_b32 v172, v120
	ds_read_u16 v160, v95
	ds_write_b128 v127, a[206:209]
	s_waitcnt lgkmcnt(1)
	v_ashrrev_i32_e32 v93, 31, v161
	v_or_b32_e32 v93, 0x80000000, v93
	v_xor_b32_e32 v108, v161, v93
	v_ashrrev_i32_e32 v94, 31, v162
	v_or_b32_e32 v94, 0x80000000, v94
	v_xor_b32_e32 v109, v162, v94
	v_ashrrev_i32_e32 v93, 31, v163
	v_or_b32_e32 v93, 0x80000000, v93
	v_xor_b32_e32 v110, v163, v93
	v_ashrrev_i32_e32 v94, 31, v164
	v_or_b32_e32 v94, 0x80000000, v94
	v_xor_b32_e32 v111, v164, v94
	v_ashrrev_i32_e32 v93, 31, v165
	v_or_b32_e32 v93, 0x80000000, v93
	v_xor_b32_e32 v112, v165, v93
	v_ashrrev_i32_e32 v94, 31, v166
	v_or_b32_e32 v94, 0x80000000, v94
	v_xor_b32_e32 v113, v166, v94
	v_ashrrev_i32_e32 v93, 31, v167
	v_or_b32_e32 v93, 0x80000000, v93
	v_xor_b32_e32 v114, v167, v93
	v_ashrrev_i32_e32 v94, 31, v168
	v_or_b32_e32 v94, 0x80000000, v94
	v_xor_b32_e32 v115, v168, v94
	v_ashrrev_i32_e32 v93, 31, v169
	v_or_b32_e32 v93, 0x80000000, v93
	v_xor_b32_e32 v116, v169, v93
	v_ashrrev_i32_e32 v94, 31, v170
	v_or_b32_e32 v94, 0x80000000, v94
	v_xor_b32_e32 v117, v170, v94
	v_ashrrev_i32_e32 v93, 31, v171
	v_or_b32_e32 v93, 0x80000000, v93
	v_xor_b32_e32 v118, v171, v93
	v_ashrrev_i32_e32 v94, 31, v172
	v_or_b32_e32 v94, 0x80000000, v94
	v_xor_b32_e32 v119, v172, v94
	v_max3_u32 v92, v108, v109, v110
	v_min3_u32 v93, v108, v109, v110
	v_max3_u32 v92, v111, v112, v92
	v_min3_u32 v93, v111, v112, v93
	v_max3_u32 v92, v113, v114, v92
	v_min3_u32 v93, v113, v114, v93
	v_max3_u32 v92, v115, v116, v92
	v_min3_u32 v93, v115, v116, v93
	v_max3_u32 v92, v117, v118, v92
	v_min3_u32 v93, v117, v118, v93
	v_max_u32_e32 v92, v119, v92
	v_min_u32_e32 v93, v119, v93
	s_nop 0
	v_max_u32_dpp v92, v92, v92 quad_perm:[1,0,3,2] row_mask:0xf bank_mask:0xf bound_ctrl:1
	v_min_u32_dpp v93, v93, v93 quad_perm:[1,0,3,2] row_mask:0xf bank_mask:0xf bound_ctrl:1
	s_nop 0
	v_max_u32_dpp v92, v92, v92 quad_perm:[2,3,0,1] row_mask:0xf bank_mask:0xf bound_ctrl:1
	v_min_u32_dpp v93, v93, v93 quad_perm:[2,3,0,1] row_mask:0xf bank_mask:0xf bound_ctrl:1
	s_nop 0
	v_max_u32_dpp v92, v92, v92 row_half_mirror row_mask:0xf bank_mask:0xf bound_ctrl:1
	v_min_u32_dpp v93, v93, v93 row_half_mirror row_mask:0xf bank_mask:0xf bound_ctrl:1
	s_nop 0
	v_max_u32_dpp v92, v92, v92 row_mirror row_mask:0xf bank_mask:0xf bound_ctrl:1
	v_min_u32_dpp v93, v93, v93 row_mirror row_mask:0xf bank_mask:0xf bound_ctrl:1
	s_nop 1
	v_readlane_b32 s15, v92, 0
	v_readlane_b32 s16, v92, 16
	v_readlane_b32 s17, v92, 32
	v_readlane_b32 s18, v92, 48
	s_max_u32 s15, s15, s16
	s_max_u32 s17, s17, s18
	s_max_u32 s15, s15, s17
	v_readlane_b32 s16, v93, 0
	v_readlane_b32 s17, v93, 16
	v_readlane_b32 s18, v93, 32
	v_readlane_b32 s19, v93, 48
	s_min_u32 s16, s16, s17
	s_min_u32 s18, s18, s19
	s_min_u32 s16, s16, s18
	s_sub_u32 s17, s15, 0x3000000
	s_cselect_b32 s17, 0, s17
	s_max_u32 s14, s16, s17
	s_sub_u32 s16, s15, s14
	s_add_u32 s16, s16, 1
	s_cmpk_le_u32 s16, 0x100
	s_cbranch_scc1 .Lpr_orig
	v_mov_b32_e32 v92, s16
	v_cvt_f32_u32_e32 v92, v92
	v_rcp_f32_e32 v92, v92
	s_nop 0
	v_mul_f32_e32 v92, 0x53800000, v92
	v_cvt_u32_f32_e32 v92, v92
	s_nop 0
	v_readfirstlane_b32 s21, v92
	s_nop 1
	v_max_u32_e32 v93, s14, v108
	v_subrev_u32_e32 v93, s14, v93
	v_mul_hi_u32 v93, v93, s21
	v_min_u32_e32 v173, 0xff, v93
	v_max_u32_e32 v94, s14, v109
	v_subrev_u32_e32 v94, s14, v94
	v_mul_hi_u32 v94, v94, s21
	v_min_u32_e32 v174, 0xff, v94
	v_max_u32_e32 v95, s14, v110
	v_subrev_u32_e32 v95, s14, v95
	v_mul_hi_u32 v95, v95, s21
	v_min_u32_e32 v175, 0xff, v95
	v_max_u32_e32 v93, s14, v111
	v_subrev_u32_e32 v93, s14, v93
	v_mul_hi_u32 v93, v93, s21
	v_min_u32_e32 v176, 0xff, v93
	v_max_u32_e32 v94, s14, v112
	v_subrev_u32_e32 v94, s14, v94
	v_mul_hi_u32 v94, v94, s21
	v_min_u32_e32 v177, 0xff, v94
	v_max_u32_e32 v95, s14, v113
	v_subrev_u32_e32 v95, s14, v95
	v_mul_hi_u32 v95, v95, s21
	v_min_u32_e32 v178, 0xff, v95
	v_max_u32_e32 v93, s14, v114
	v_subrev_u32_e32 v93, s14, v93
	v_mul_hi_u32 v93, v93, s21
	v_min_u32_e32 v179, 0xff, v93
	v_max_u32_e32 v94, s14, v115
	v_subrev_u32_e32 v94, s14, v94
	v_mul_hi_u32 v94, v94, s21
	v_min_u32_e32 v180, 0xff, v94
	v_max_u32_e32 v95, s14, v116
	v_subrev_u32_e32 v95, s14, v95
	v_mul_hi_u32 v95, v95, s21
	v_min_u32_e32 v181, 0xff, v95
	v_max_u32_e32 v93, s14, v117
	v_subrev_u32_e32 v93, s14, v93
	v_mul_hi_u32 v93, v93, s21
	v_min_u32_e32 v182, 0xff, v93
	v_max_u32_e32 v94, s14, v118
	v_subrev_u32_e32 v94, s14, v94
	v_mul_hi_u32 v94, v94, s21
	v_min_u32_e32 v183, 0xff, v94
	v_max_u32_e32 v95, s14, v119
	v_subrev_u32_e32 v95, s14, v95
	v_mul_hi_u32 v95, v95, s21
	v_min_u32_e32 v184, 0xff, v95
	v_cmp_gt_u32_e64 s[26:27], s12, v6
	v_cmp_gt_u32_e64 s[28:29], s12, v7
	v_cmp_gt_u32_e64 s[30:31], s12, v4
	v_cndmask_b32_e64 v181, 0, v181, s[26:27]
	v_cmp_gt_u32_e64 s[26:27], s12, v5
	v_cndmask_b32_e64 v182, 0, v182, s[28:29]
	s_nop 0
	v_cndmask_b32_e64 v183, 0, v183, s[30:31]
	v_cndmask_b32_e64 v184, 0, v184, s[26:27]
	s_mov_b64 s[22:23], exec
	v_cmp_ne_u32_e64 s[26:27], 0, v173
	v_lshl_add_u32 v93, v173, 2, v121
	s_mov_b64 exec, s[26:27]
	ds_add_u32 v93, v252
	s_mov_b64 exec, s[22:23]
	v_cmp_ne_u32_e64 s[28:29], 0, v174
	v_lshl_add_u32 v94, v174, 2, v121
	s_mov_b64 exec, s[28:29]
	ds_add_u32 v94, v252
	s_mov_b64 exec, s[22:23]
	v_cmp_ne_u32_e64 s[30:31], 0, v175
	v_lshl_add_u32 v95, v175, 2, v121
	s_mov_b64 exec, s[30:31]
	ds_add_u32 v95, v252
	s_mov_b64 exec, s[22:23]
	v_cmp_ne_u32_e64 s[26:27], 0, v176
	v_lshl_add_u32 v93, v176, 2, v121
	s_mov_b64 exec, s[26:27]
	ds_add_u32 v93, v252
	s_mov_b64 exec, s[22:23]
	v_cmp_ne_u32_e64 s[28:29], 0, v177
	v_lshl_add_u32 v94, v177, 2, v121
	s_mov_b64 exec, s[28:29]
	ds_add_u32 v94, v252
	s_mov_b64 exec, s[22:23]
	v_cmp_ne_u32_e64 s[30:31], 0, v178
	v_lshl_add_u32 v95, v178, 2, v121
	s_mov_b64 exec, s[30:31]
	ds_add_u32 v95, v252
	s_mov_b64 exec, s[22:23]
	v_cmp_ne_u32_e64 s[26:27], 0, v179
	v_lshl_add_u32 v93, v179, 2, v121
	s_mov_b64 exec, s[26:27]
	ds_add_u32 v93, v252
	s_mov_b64 exec, s[22:23]
	v_cmp_ne_u32_e64 s[28:29], 0, v180
	v_lshl_add_u32 v94, v180, 2, v121
	s_mov_b64 exec, s[28:29]
	ds_add_u32 v94, v252
	s_mov_b64 exec, s[22:23]
	v_cmp_ne_u32_e64 s[30:31], 0, v181
	v_lshl_add_u32 v95, v181, 2, v121
	s_mov_b64 exec, s[30:31]
	ds_add_u32 v95, v252
	s_mov_b64 exec, s[22:23]
	v_cmp_ne_u32_e64 s[26:27], 0, v182
	v_lshl_add_u32 v93, v182, 2, v121
	s_mov_b64 exec, s[26:27]
	ds_add_u32 v93, v252
	s_mov_b64 exec, s[22:23]
	v_cmp_ne_u32_e64 s[28:29], 0, v183
	v_lshl_add_u32 v94, v183, 2, v121
	s_mov_b64 exec, s[28:29]
	ds_add_u32 v94, v252
	s_mov_b64 exec, s[22:23]
	v_cmp_ne_u32_e64 s[30:31], 0, v184
	v_lshl_add_u32 v95, v184, 2, v121
	s_mov_b64 exec, s[30:31]
	ds_add_u32 v95, v252
	s_mov_b64 exec, s[22:23]
	ds_read_b128 v[92:95], v127
	s_waitcnt lgkmcnt(0)
	v_add_u32_e32 v120, v92, v93
	v_add3_u32 v120, v120, v94, v95
	v_mov_b32_e32 v122, v120
	s_nop 1
	v_add_u32_dpp v122, v122, v122 row_shr:1 row_mask:0xf bank_mask:0xf bound_ctrl:1
	s_nop 1
	v_add_u32_dpp v122, v122, v122 row_shr:2 row_mask:0xf bank_mask:0xf bound_ctrl:1
	s_nop 1
	v_add_u32_dpp v122, v122, v122 row_shr:4 row_mask:0xf bank_mask:0xf bound_ctrl:1
	s_nop 1
	v_add_u32_dpp v122, v122, v122 row_shr:8 row_mask:0xf bank_mask:0xf bound_ctrl:1
	s_nop 1
	v_add_u32_dpp v122, v122, v122 row_bcast:15 row_mask:0xa bank_mask:0xf
	s_nop 1
	v_add_u32_dpp v122, v122, v122 row_bcast:31 row_mask:0xc bank_mask:0xf
	s_nop 1
	v_readlane_b32 s16, v122, 63
	s_nop 1
	v_sub_u32_e32 v123, s16, v122
	v_add_u32_e32 v124, v123, v95
	v_add_u32_e32 v126, v124, v94
	v_add_u32_e32 v128, v126, v93
	v_add_u32_e32 v129, v128, v92
	s_movk_i32 s17, 0x100
	v_lshlrev_b32_e32 v130, 2, v190
	v_cmp_le_u32_e64 s[26:27], s17, v128
	v_cmp_le_u32_e64 s[28:29], s17, v126
	v_cmp_le_u32_e64 s[30:31], s17, v124
	v_mov_b32_e32 v134, v130
	v_or_b32_e32 v131, 1, v134
	v_cndmask_b32_e64 v129, v129, v128, s[26:27]
	v_cndmask_b32_e64 v130, v130, v131, s[26:27]
	v_or_b32_e32 v131, 2, v134
	v_cndmask_b32_e64 v129, v129, v126, s[28:29]
	v_cndmask_b32_e64 v130, v130, v131, s[28:29]
	v_or_b32_e32 v131, 3, v134
	v_cndmask_b32_e64 v129, v129, v124, s[30:31]
	v_cndmask_b32_e64 v130, v130, v131, s[30:31]
	v_add_u32_e32 v132, v123, v120
	v_cmp_gt_u32_e64 s[26:27], s17, v123
	v_cmp_le_u32_e64 s[28:29], s17, v132
	s_nop 0
	s_and_b64 s[26:27], s[26:27], s[28:29]
	s_cmp_eq_u64 s[26:27], 0
	s_cbranch_scc1 .Lpr_orig
	s_ff1_i32_b64 s18, s[26:27]
	s_nop 3
	v_readlane_b32 s19, v129, s18
	v_readlane_b32 s20, v130, s18
	s_cmpk_gt_u32 s19, 0x140
	s_cbranch_scc1 .Lpr_orig
	s_cmp_eq_u32 s20, 0
	s_cbranch_scc1 .Lpr_orig
	v_mov_b32_e32 v92, s21
	v_cvt_f32_u32_e32 v92, v92
	v_rcp_f32_e32 v92, v92
	v_mov_b32_e32 v93, s20
	v_cvt_f32_u32_e32 v93, v93
	v_mul_f32_e32 v92, 0x4f800000, v92
	v_mul_f32_e32 v92, v92, v93
	v_mul_f32_e32 v92, 0x3f7ffff0, v92
	v_cvt_u32_f32_e32 v92, v92
	s_nop 0
	v_readfirstlane_b32 s16, v92
	s_add_u32 s16, s16, s14
	v_mov_b32_e32 v120, 0
	v_cmp_le_u32_e64 s[26:27], s20, v173
	v_cmp_le_u32_e64 s[28:29], s20, v174
	v_cmp_le_u32_e64 s[30:31], s20, v175
	v_addc_co_u32_e64 v120, vcc, 0, v120, s[26:27]
	v_cmp_le_u32_e64 s[26:27], s20, v176
	v_addc_co_u32_e64 v120, vcc, 0, v120, s[28:29]
	v_cmp_le_u32_e64 s[28:29], s20, v177
	v_addc_co_u32_e64 v120, vcc, 0, v120, s[30:31]
	v_cmp_le_u32_e64 s[30:31], s20, v178
	v_addc_co_u32_e64 v120, vcc, 0, v120, s[26:27]
	v_cmp_le_u32_e64 s[26:27], s20, v179
	v_addc_co_u32_e64 v120, vcc, 0, v120, s[28:29]
	v_cmp_le_u32_e64 s[28:29], s20, v180
	v_addc_co_u32_e64 v120, vcc, 0, v120, s[30:31]
	v_cmp_le_u32_e64 s[30:31], s20, v181
	v_addc_co_u32_e64 v120, vcc, 0, v120, s[26:27]
	v_cmp_le_u32_e64 s[26:27], s20, v182
	v_addc_co_u32_e64 v120, vcc, 0, v120, s[28:29]
	v_cmp_le_u32_e64 s[28:29], s20, v183
	v_addc_co_u32_e64 v120, vcc, 0, v120, s[30:31]
	v_cmp_le_u32_e64 s[30:31], s20, v184
	v_addc_co_u32_e64 v120, vcc, 0, v120, s[26:27]
	s_nop 0
	v_addc_co_u32_e64 v120, vcc, 0, v120, s[28:29]
	v_addc_co_u32_e64 v120, vcc, 0, v120, s[30:31]
	v_mov_b32_e32 v122, v120
	s_nop 1
	v_add_u32_dpp v122, v122, v122 row_shr:1 row_mask:0xf bank_mask:0xf bound_ctrl:1
	s_nop 1
	v_add_u32_dpp v122, v122, v122 row_shr:2 row_mask:0xf bank_mask:0xf bound_ctrl:1
	s_nop 1
	v_add_u32_dpp v122, v122, v122 row_shr:4 row_mask:0xf bank_mask:0xf bound_ctrl:1
	s_nop 1
	v_add_u32_dpp v122, v122, v122 row_shr:8 row_mask:0xf bank_mask:0xf bound_ctrl:1
	s_nop 1
	v_add_u32_dpp v122, v122, v122 row_bcast:15 row_mask:0xa bank_mask:0xf
	s_nop 1
	v_add_u32_dpp v122, v122, v122 row_bcast:31 row_mask:0xc bank_mask:0xf
	s_nop 1
	v_sub_u32_e32 v122, v122, v120
	s_mov_b64 s[22:23], exec
	v_cmp_le_u32_e64 s[26:27], s20, v173
	s_mov_b64 exec, s[26:27]
	s_cbranch_execz .Lpr_w0
	v_lshl_add_u32 v93, v122, 2, s9
	v_lshl_add_u32 v94, v122, 1, s10
	ds_write_b32 v93, v161
	ds_write_b16 v94, v142
	v_add_u32_e32 v122, 1, v122
.Lpr_w0:
	s_mov_b64 exec, s[22:23]
	v_cmp_le_u32_e64 s[26:27], s20, v174
	s_mov_b64 exec, s[26:27]
	s_cbranch_execz .Lpr_w1
	v_lshl_add_u32 v93, v122, 2, s9
	v_lshl_add_u32 v94, v122, 1, s10
	ds_write_b32 v93, v162
	ds_write_b16 v94, v143
	v_add_u32_e32 v122, 1, v122
.Lpr_w1:
	s_mov_b64 exec, s[22:23]
	v_cmp_le_u32_e64 s[26:27], s20, v175
	s_mov_b64 exec, s[26:27]
	s_cbranch_execz .Lpr_w2
	v_lshl_add_u32 v93, v122, 2, s9
	v_lshl_add_u32 v94, v122, 1, s10
	ds_write_b32 v93, v163
	ds_write_b16 v94, v144
	v_add_u32_e32 v122, 1, v122
.Lpr_w2:
	s_mov_b64 exec, s[22:23]
	v_cmp_le_u32_e64 s[26:27], s20, v176
	s_mov_b64 exec, s[26:27]
	s_cbranch_execz .Lpr_w3
	v_lshl_add_u32 v93, v122, 2, s9
	v_lshl_add_u32 v94, v122, 1, s10
	ds_write_b32 v93, v164
	ds_write_b16 v94, v145
	v_add_u32_e32 v122, 1, v122
.Lpr_w3:
	s_mov_b64 exec, s[22:23]
	v_cmp_le_u32_e64 s[26:27], s20, v177
	s_mov_b64 exec, s[26:27]
	s_cbranch_execz .Lpr_w4
	v_lshl_add_u32 v93, v122, 2, s9
	v_lshl_add_u32 v94, v122, 1, s10
	ds_write_b32 v93, v165
	ds_write_b16 v94, v146
	v_add_u32_e32 v122, 1, v122
.Lpr_w4:
	s_mov_b64 exec, s[22:23]
	v_cmp_le_u32_e64 s[26:27], s20, v178
	s_mov_b64 exec, s[26:27]
	s_cbranch_execz .Lpr_w5
	v_lshl_add_u32 v93, v122, 2, s9
	v_lshl_add_u32 v94, v122, 1, s10
	ds_write_b32 v93, v166
	ds_write_b16 v94, v148
	v_add_u32_e32 v122, 1, v122
.Lpr_w5:
	s_mov_b64 exec, s[22:23]
	v_cmp_le_u32_e64 s[26:27], s20, v179
	s_mov_b64 exec, s[26:27]
	s_cbranch_execz .Lpr_w6
	v_lshl_add_u32 v93, v122, 2, s9
	v_lshl_add_u32 v94, v122, 1, s10
	ds_write_b32 v93, v167
	ds_write_b16 v94, v149
	v_add_u32_e32 v122, 1, v122
.Lpr_w6:
	s_mov_b64 exec, s[22:23]
	v_cmp_le_u32_e64 s[26:27], s20, v180
	s_mov_b64 exec, s[26:27]
	s_cbranch_execz .Lpr_w7
	v_lshl_add_u32 v93, v122, 2, s9
	v_lshl_add_u32 v94, v122, 1, s10
	ds_write_b32 v93, v168
	ds_write_b16 v94, v150
	v_add_u32_e32 v122, 1, v122
.Lpr_w7:
	s_mov_b64 exec, s[22:23]
	v_cmp_le_u32_e64 s[26:27], s20, v181
	s_mov_b64 exec, s[26:27]
	s_cbranch_execz .Lpr_w8
	v_lshl_add_u32 v93, v122, 2, s9
	v_lshl_add_u32 v94, v122, 1, s10
	ds_write_b32 v93, v169
	ds_write_b16 v94, v152
	v_add_u32_e32 v122, 1, v122
.Lpr_w8:
	s_mov_b64 exec, s[22:23]
	v_cmp_le_u32_e64 s[26:27], s20, v182
	s_mov_b64 exec, s[26:27]
	s_cbranch_execz .Lpr_w9
	v_lshl_add_u32 v93, v122, 2, s9
	v_lshl_add_u32 v94, v122, 1, s10
	ds_write_b32 v93, v170
	ds_write_b16 v94, v153
	v_add_u32_e32 v122, 1, v122
.Lpr_w9:
	s_mov_b64 exec, s[22:23]
	v_cmp_le_u32_e64 s[26:27], s20, v183
	s_mov_b64 exec, s[26:27]
	s_cbranch_execz .Lpr_w10
	v_lshl_add_u32 v93, v122, 2, s9
	v_lshl_add_u32 v94, v122, 1, s10
	ds_write_b32 v93, v171
	ds_write_b16 v94, v159
	v_add_u32_e32 v122, 1, v122
.Lpr_w10:
	s_mov_b64 exec, s[22:23]
	v_cmp_le_u32_e64 s[26:27], s20, v184
	s_mov_b64 exec, s[26:27]
	s_cbranch_execz .Lpr_w11
	v_lshl_add_u32 v93, v122, 2, s9
	v_lshl_add_u32 v94, v122, 1, s10
	ds_write_b32 v93, v172
	ds_write_b16 v94, v160
	v_add_u32_e32 v122, 1, v122
.Lpr_w11:
	s_mov_b64 exec, s[22:23]
	s_bitcmp1_b32 s16, 31
	s_cselect_b32 s17, 0x80000000, -1
	s_xor_b32 s17, s16, s17
	s_mov_b64 exec, s[58:59]
	v_mov_b32_e32 v40, s11
	v_mov_b32_e32 v92, s19
	v_mov_b32_e32 v93, s17
	ds_write_b32 v40, v92
	ds_write_b32 v40, v93 offset:128
	s_mov_b64 exec, s[22:23]
	s_branch .LBB0_143
.Lpr_orig:
	s_ff1_i32_b32 s8, s6
	s_mul_i32 s9, s8, 0x300
	s_lshl_b32 s8, s8, 2
	s_add_i32 s74, s8, 0
	s_add_i32 s76, s74, 0x24000
	v_mov_b32_e32 v40, s76
	s_waitcnt vmcnt(7)
	ds_read_b32 v92, v40
	s_lshl_b32 s10, s9, 2
	s_lshl_b32 s8, s9, 1
	s_add_i32 s65, s10, 0
	s_add_i32 s69, s8, 0
	s_waitcnt lgkmcnt(0)
	v_cmp_lt_i32_e64 s[8:9], v190, v92
	v_cmp_lt_i32_e64 s[10:11], v185, v92
	v_cmp_lt_i32_e64 s[12:13], v192, v92
	v_cmp_lt_i32_e64 s[14:15], v191, v92
	s_add_i32 s69, s69, 0x18000
	v_cndmask_b32_e64 v40, 0, v190, s[8:9]
	v_cndmask_b32_e64 v94, 0, v185, s[10:11]
	s_waitcnt vmcnt(6)
	v_cndmask_b32_e64 v108, 0, v192, s[12:13]
	v_cndmask_b32_e64 v110, 0, v191, s[14:15]
	v_lshl_add_u32 v93, v40, 2, s65
	v_lshl_add_u32 v40, v40, 1, s69
	v_lshl_add_u32 v95, v94, 2, s65
	v_lshl_add_u32 v94, v94, 1, s69
	v_lshl_add_u32 v109, v108, 2, s65
	v_lshl_add_u32 v108, v108, 1, s69
	v_lshl_add_u32 v111, v110, 2, s65
	v_lshl_add_u32 v110, v110, 1, s69
	ds_read_b32 v93, v93
	s_waitcnt vmcnt(5)
	ds_read_u16 v112, v40
	ds_read_b32 v95, v95
	ds_read_u16 v94, v94
	ds_read_b32 v109, v109
	ds_read_u16 v108, v108
	ds_read_b32 v111, v111
	ds_read_u16 v113, v110
	s_waitcnt lgkmcnt(7)
	v_cndmask_b32_e64 v40, 0, v93, s[8:9]
	v_not_b32_e32 v93, v40
	v_cmp_gt_i32_e32 vcc, 0, v40
	v_mov_b32_e32 v159, 0x3fff
	v_cmp_lt_i32_e64 s[16:17], v0, v92
	v_cndmask_b32_e64 v40, -|v40|, v93, vcc
	v_lshlrev_b64 v[128:129], 14, v[40:41]
	s_waitcnt lgkmcnt(6)
	v_sub_u32_e32 v40, 0x3fff, v112
	v_cndmask_b32_e64 v124, v159, v40, s[8:9]
	s_waitcnt lgkmcnt(5)
	v_cndmask_b32_e64 v40, 0, v95, s[10:11]
	v_not_b32_e32 v93, v40
	v_cmp_gt_i32_e32 vcc, 0, v40
	v_cmp_lt_i32_e64 s[18:19], v1, v92
	v_cmp_lt_i32_e64 s[20:21], v2, v92
	v_cndmask_b32_e64 v40, -|v40|, v93, vcc
	s_waitcnt vmcnt(4)
	v_lshlrev_b64 v[118:119], 14, v[40:41]
	s_waitcnt lgkmcnt(4)
	v_sub_u32_e32 v40, 0x3fff, v94
	v_cndmask_b32_e64 v116, v159, v40, s[10:11]
	s_waitcnt lgkmcnt(3)
	v_cndmask_b32_e64 v40, 0, v109, s[12:13]
	v_not_b32_e32 v93, v40
	v_cmp_gt_i32_e32 vcc, 0, v40
	v_cmp_lt_i32_e64 s[22:23], v3, v92
	v_cndmask_b32_e64 v94, 0, v1, s[18:19]
	v_cndmask_b32_e64 v40, -|v40|, v93, vcc
	v_lshlrev_b64 v[114:115], 14, v[40:41]
	s_waitcnt lgkmcnt(2)
	v_sub_u32_e32 v40, 0x3fff, v108
	v_cndmask_b32_e64 v112, v159, v40, s[12:13]
	s_waitcnt lgkmcnt(1)
	v_cndmask_b32_e64 v40, 0, v111, s[14:15]
	v_not_b32_e32 v93, v40
	v_cmp_gt_i32_e32 vcc, 0, v40
	v_cndmask_b32_e64 v109, 0, v2, s[20:21]
	v_cndmask_b32_e64 v117, 0, v3, s[22:23]
	v_cndmask_b32_e64 v40, -|v40|, v93, vcc
	v_lshlrev_b64 v[110:111], 14, v[40:41]
	s_waitcnt lgkmcnt(0)
	v_sub_u32_e32 v40, 0x3fff, v113
	v_cndmask_b32_e64 v108, v159, v40, s[14:15]
	v_cndmask_b32_e64 v40, 0, v0, s[16:17]
	v_lshl_add_u32 v93, v40, 2, s65
	v_lshl_add_u32 v40, v40, 1, s69
	v_lshl_add_u32 v95, v94, 2, s65
	v_lshl_add_u32 v94, v94, 1, s69
	v_lshl_add_u32 v113, v109, 2, s65
	v_lshl_add_u32 v109, v109, 1, s69
	v_lshl_add_u32 v120, v117, 2, s65
	v_lshl_add_u32 v117, v117, 1, s69
	ds_read_b32 v93, v93
	ds_read_u16 v122, v40
	ds_read_b32 v95, v95
	ds_read_u16 v94, v94
	ds_read_b32 v113, v113
	ds_read_u16 v109, v109
	ds_read_b32 v120, v120
	ds_read_u16 v117, v117
	s_waitcnt lgkmcnt(7)
	v_cndmask_b32_e64 v40, 0, v93, s[16:17]
	v_not_b32_e32 v93, v40
	v_cmp_gt_i32_e32 vcc, 0, v40
	v_cmp_lt_i32_e64 s[24:25], v6, v92
	v_cmp_lt_i32_e64 s[26:27], v7, v92
	v_cndmask_b32_e64 v40, -|v40|, v93, vcc
	v_lshlrev_b64 v[142:143], 14, v[40:41]
	s_waitcnt lgkmcnt(6)
	v_sub_u32_e32 v40, 0x3fff, v122
	v_cndmask_b32_e64 v138, v159, v40, s[16:17]
	s_waitcnt lgkmcnt(5)
	v_cndmask_b32_e64 v40, 0, v95, s[18:19]
	v_not_b32_e32 v93, v40
	v_cmp_gt_i32_e32 vcc, 0, v40
	v_cmp_lt_i32_e64 s[28:29], v4, v92
	v_cmp_lt_i32_e64 s[30:31], v5, v92
	v_cndmask_b32_e64 v40, -|v40|, v93, vcc
	v_lshlrev_b64 v[134:135], 14, v[40:41]
	s_waitcnt lgkmcnt(4)
	v_sub_u32_e32 v40, 0x3fff, v94
	v_cndmask_b32_e64 v132, v159, v40, s[18:19]
	s_waitcnt lgkmcnt(3)
	v_cndmask_b32_e64 v40, 0, v113, s[20:21]
	v_not_b32_e32 v93, v40
	v_cmp_gt_i32_e32 vcc, 0, v40
	v_cndmask_b32_e64 v94, 0, v7, s[26:27]
	v_cndmask_b32_e64 v92, 0, v5, s[30:31]
	v_cndmask_b32_e64 v40, -|v40|, v93, vcc
	v_lshlrev_b64 v[130:131], 14, v[40:41]
	s_waitcnt lgkmcnt(2)
	v_sub_u32_e32 v40, 0x3fff, v109
	v_cndmask_b32_e64 v126, v159, v40, s[20:21]
	s_waitcnt lgkmcnt(1)
	v_cndmask_b32_e64 v40, 0, v120, s[22:23]
	v_not_b32_e32 v93, v40
	v_cmp_gt_i32_e32 vcc, 0, v40
	v_cndmask_b32_e64 v109, 0, v4, s[28:29]
	v_lshl_add_u32 v95, v94, 2, s65
	v_cndmask_b32_e64 v40, -|v40|, v93, vcc
	v_lshlrev_b64 v[122:123], 14, v[40:41]
	s_waitcnt lgkmcnt(0)
	v_sub_u32_e32 v40, 0x3fff, v117
	v_cndmask_b32_e64 v120, v159, v40, s[22:23]
	v_cndmask_b32_e64 v40, 0, v6, s[24:25]
	v_lshl_add_u32 v93, v40, 2, s65
	v_lshl_add_u32 v40, v40, 1, s69
	v_lshl_add_u32 v94, v94, 1, s69
	v_lshl_add_u32 v113, v109, 2, s65
	v_lshl_add_u32 v109, v109, 1, s69
	v_lshl_add_u32 v117, v92, 2, s65
	v_lshl_add_u32 v92, v92, 1, s69
	ds_read_b32 v93, v93
	ds_read_u16 v136, v40
	ds_read_b32 v95, v95
	ds_read_u16 v94, v94
	ds_read_b32 v113, v113
	ds_read_u16 v109, v109
	ds_read_b32 v117, v117
	ds_read_u16 v92, v92
	s_waitcnt lgkmcnt(7)
	v_cndmask_b32_e64 v40, 0, v93, s[24:25]
	v_not_b32_e32 v93, v40
	v_cmp_gt_i32_e32 vcc, 0, v40
	v_or_b32_e32 v128, v128, v124
	v_or_b32_e32 v118, v118, v116
	v_cndmask_b32_e64 v40, -|v40|, v93, vcc
	v_lshlrev_b64 v[152:153], 14, v[40:41]
	s_waitcnt lgkmcnt(6)
	v_sub_u32_e32 v40, 0x3fff, v136
	v_cndmask_b32_e64 v150, v159, v40, s[24:25]
	s_waitcnt lgkmcnt(5)
	v_cndmask_b32_e64 v40, 0, v95, s[26:27]
	v_not_b32_e32 v93, v40
	v_cmp_gt_i32_e32 vcc, 0, v40
	v_readfirstlane_b32 s88, v128
	v_or_b32_e32 v114, v114, v112
	v_cndmask_b32_e64 v40, -|v40|, v93, vcc
	v_lshlrev_b64 v[148:149], 14, v[40:41]
	s_waitcnt lgkmcnt(4)
	v_sub_u32_e32 v40, 0x3fff, v94
	v_cndmask_b32_e64 v146, v159, v40, s[26:27]
	s_waitcnt lgkmcnt(3)
	v_cndmask_b32_e64 v40, 0, v113, s[28:29]
	v_not_b32_e32 v93, v40
	v_cmp_gt_i32_e32 vcc, 0, v40
	v_xor_b32_e32 v95, s88, v118
	v_or_b32_e32 v110, v110, v108
	v_cndmask_b32_e64 v40, -|v40|, v93, vcc
	v_lshlrev_b64 v[144:145], 14, v[40:41]
	s_waitcnt lgkmcnt(2)
	v_sub_u32_e32 v40, 0x3fff, v109
	v_cndmask_b32_e64 v140, v159, v40, s[28:29]
	s_waitcnt lgkmcnt(1)
	v_cndmask_b32_e64 v40, 0, v117, s[30:31]
	v_not_b32_e32 v93, v40
	v_cmp_gt_i32_e32 vcc, 0, v40
	v_cndmask_b32_e64 v95, 0, v95, s[10:11]
	v_readfirstlane_b32 s89, v129
	v_cndmask_b32_e64 v40, -|v40|, v93, vcc
	v_xor_b32_e32 v93, s88, v128
	v_cndmask_b32_e64 v93, 0, v93, s[8:9]
	v_or_b32_e32 v93, v95, v93
	v_xor_b32_e32 v95, s88, v114
	v_xor_b32_e32 v113, s88, v110
	v_or_b32_e32 v142, v142, v138
	v_or_b32_e32 v134, v134, v132
	v_lshlrev_b64 v[136:137], 14, v[40:41]
	s_waitcnt lgkmcnt(0)
	v_sub_u32_e32 v40, 0x3fff, v92
	v_xor_b32_e32 v92, s89, v129
	v_xor_b32_e32 v94, s89, v119
	v_cndmask_b32_e64 v95, 0, v95, s[12:13]
	v_cndmask_b32_e64 v113, 0, v113, s[14:15]
	v_cndmask_b32_e64 v92, 0, v92, s[8:9]
	v_cndmask_b32_e64 v94, 0, v94, s[10:11]
	v_or3_b32 v93, v93, v95, v113
	v_xor_b32_e32 v95, s88, v142
	v_xor_b32_e32 v113, s88, v134
	v_or_b32_e32 v130, v130, v126
	v_or_b32_e32 v122, v122, v120
	v_or_b32_e32 v92, v94, v92
	v_xor_b32_e32 v94, s89, v115
	v_xor_b32_e32 v109, s89, v111
	v_cndmask_b32_e64 v95, 0, v95, s[16:17]
	v_cndmask_b32_e64 v113, 0, v113, s[18:19]
	v_cndmask_b32_e64 v94, 0, v94, s[12:13]
	v_cndmask_b32_e64 v109, 0, v109, s[14:15]
	v_or3_b32 v93, v93, v95, v113
	v_xor_b32_e32 v95, s88, v130
	v_xor_b32_e32 v113, s88, v122
	v_or_b32_e32 v152, v152, v150
	v_or_b32_e32 v148, v148, v146
	v_or3_b32 v92, v92, v94, v109
	v_xor_b32_e32 v94, s89, v143
	v_xor_b32_e32 v109, s89, v135
	v_cndmask_b32_e64 v95, 0, v95, s[20:21]
	v_cndmask_b32_e64 v113, 0, v113, s[22:23]
	v_cndmask_b32_e64 v40, v159, v40, s[30:31]
	v_cndmask_b32_e64 v94, 0, v94, s[16:17]
	v_cndmask_b32_e64 v109, 0, v109, s[18:19]
	v_or3_b32 v93, v93, v95, v113
	v_xor_b32_e32 v95, s88, v152
	v_xor_b32_e32 v113, s88, v148
	v_or_b32_e32 v144, v144, v140
	v_or_b32_e32 v136, v136, v40
	v_or3_b32 v92, v92, v94, v109
	v_xor_b32_e32 v94, s89, v131
	v_xor_b32_e32 v109, s89, v123
	v_cndmask_b32_e64 v95, 0, v95, s[24:25]
	v_cndmask_b32_e64 v113, 0, v113, s[26:27]
	v_cndmask_b32_e64 v94, 0, v94, s[20:21]
	v_cndmask_b32_e64 v109, 0, v109, s[22:23]
	v_or3_b32 v93, v93, v95, v113
	v_xor_b32_e32 v95, s88, v144
	v_xor_b32_e32 v113, s88, v136
	v_or3_b32 v92, v92, v94, v109
	v_xor_b32_e32 v94, s89, v153
	v_xor_b32_e32 v109, s89, v149
	v_cndmask_b32_e64 v95, 0, v95, s[28:29]
	v_cndmask_b32_e64 v113, 0, v113, s[30:31]
	v_cndmask_b32_e64 v94, 0, v94, s[24:25]
	v_cndmask_b32_e64 v109, 0, v109, s[26:27]
	v_or3_b32 v93, v93, v95, v113
	v_or3_b32 v92, v92, v94, v109
	v_xor_b32_e32 v94, s89, v145
	v_xor_b32_e32 v109, s89, v137
	v_or_b32_dpp v93, v93, v93 quad_perm:[1,0,3,2] row_mask:0xf bank_mask:0xf bound_ctrl:1
	v_cndmask_b32_e64 v94, 0, v94, s[28:29]
	v_cndmask_b32_e64 v109, 0, v109, s[30:31]
	v_or_b32_dpp v93, v93, v93 quad_perm:[2,3,0,1] row_mask:0xf bank_mask:0xf bound_ctrl:1
	v_or3_b32 v92, v92, v94, v109
	v_cndmask_b32_e64 v166, 0, 1, s[10:11]
	v_or_b32_dpp v93, v93, v93 row_half_mirror row_mask:0xf bank_mask:0xf bound_ctrl:1
	v_or_b32_dpp v92, v92, v92 quad_perm:[1,0,3,2] row_mask:0xf bank_mask:0xf bound_ctrl:1
	v_lshlrev_b16_e32 v94, 8, v166
	v_or_b32_dpp v93, v93, v93 row_mirror row_mask:0xf bank_mask:0xf bound_ctrl:1
	v_or_b32_dpp v92, v92, v92 quad_perm:[2,3,0,1] row_mask:0xf bank_mask:0xf bound_ctrl:1
	v_readlane_b32 s34, v93, 0
	v_readlane_b32 s35, v93, 16
	s_or_b32 s34, s35, s34
	v_readlane_b32 s35, v93, 32
	v_or_b32_dpp v92, v92, v92 row_half_mirror row_mask:0xf bank_mask:0xf bound_ctrl:1
	s_or_b32 s34, s34, s35
	v_readlane_b32 s35, v93, 48
	v_or_b32_dpp v92, v92, v92 row_mirror row_mask:0xf bank_mask:0xf bound_ctrl:1
	s_or_b32 s34, s34, s35
	v_readlane_b32 s35, v92, 0
	v_readlane_b32 s36, v92, 16
	s_or_b32 s35, s36, s35
	v_readlane_b32 s36, v92, 32
	s_or_b32 s35, s35, s36
	v_readlane_b32 s36, v92, 48
	s_or_b32 s35, s35, s36
	v_cndmask_b32_e64 v95, 0, 1, s[8:9]
	v_cndmask_b32_e64 v164, 0, 1, s[14:15]
	s_flbit_i32_b64 s36, s[34:35]
	v_or_b32_e32 v168, v95, v94
	v_lshlrev_b16_e32 v94, 8, v164
	v_cndmask_b32_e64 v95, 0, 1, s[12:13]
	v_cndmask_b32_e64 v162, 0, 1, s[18:19]
	s_sub_i32 s36, 56, s36
	v_or_b32_e32 v167, v95, v94
	v_lshlrev_b16_e32 v94, 8, v162
	v_cndmask_b32_e64 v95, 0, 1, s[16:17]
	v_cndmask_b32_e64 v117, 0, 1, s[26:27]
	s_max_i32 s36, s36, 0
	v_or_b32_e32 v165, v95, v94
	v_lshlrev_b16_e32 v94, 8, v117
	v_cndmask_b32_e64 v95, 0, 1, s[24:25]
	s_cmp_lg_u64 s[34:35], 0
	s_mov_b32 s70, s60
	s_mov_b32 s90, 0
	v_or_b32_e32 v160, v95, v94
	v_cndmask_b32_e64 v109, 0, 1, s[30:31]
	v_cndmask_b32_e64 v113, 0, 1, s[28:29]
	v_cndmask_b32_e64 v161, 0, 1, s[22:23]
	v_cndmask_b32_e64 v163, 0, 1, s[20:21]
	s_cselect_b32 s79, s36, 0
	s_mov_b64 s[94:95], 0
	s_movk_i32 s72, 0x100
	v_mov_b32_e32 v159, 7
	s_mov_b32 s77, 0
	s_mov_b32 s73, 0
